# FoX: first four cumulative-gate reads issued with the K reads; post-asm s_nop dropped in the row-max chain
# baseline (speedup 1.0000x reference)
; __device__ __forceinline__ f32x16 mfma32(bf16x8 a, bf16x8 b, f32x16 c) { return __builtin_amdgcn_mfma_f32_32x32x16_bf16(a, b, c, 0, 0, 0); }
; template <int MODE> ...
;     ...
;         const lptr Kt = L + A_KT + buf * 9216, Vt = L + A_VT + vcur * 12288;
;         f32x16 s0, s1;
; #pragma unroll
;         for (int s4 = 0; s4 < 4; ++s4) {
;             const bf16x8 a0 = lds_ld<bf16x8>(Kt + n * KP + s4 * 32 + hl * 16);
;             const bf16x8 a1 = lds_ld<bf16x8>(Kt + (32 + n) * KP + s4 * 32 + hl * 16);
;             if (s4 == 0) { s0 = mfma32(a0, qf[0], negm); s1 = mfma32(a1, qf[0], negm); }
;             else { s0 = mfma32(a0, qf[s4], s0); s1 = mfma32(a1, qf[s4], s1); }
;         }
;         const int kbase = 64 * kt + 4 * hl;
;         const bool far = (MODE == MODE_WIN || MODE == MODE_SEL) ? (wtmin - (64 * kt + 63) >= 128) : false;
;         const bool fmask = (MODE == MODE_FOX) ? (64 * kt + 63 > wtmin) : false;
;         const bool clean = (MODE == MODE_WIN) ? (far && (wtmax - 64 * kt < W)) : false;
;         const float mref = (MODE == MODE_CMP2) ? mfix : ((m == -INFINITY) ? 0.f : m);
;         if (MODE == MODE_FOX) {
; #pragma unroll
;             for (int kb = 0; kb < 2; ++kb)
; #pragma unroll
;                 for (int a = 0; a < 4; ++a) {
;                     const f32x4 c4 = lds_ld<f32x4>(L + A_CB + buf * 256 + (32 * kb + 8 * a + 4 * hl) * 4);
; #pragma unroll
;                     for (int e = 0; e < 4; ++e) { const int r = 4 * a + e; if (kb) s1[r] = s1[r] * SC2 + c4[e]; else s0[r] = s0[r] * SC2 + c4[e]; }
;                 }
;             if (__builtin_amdgcn_readfirstlane((int)fmask)) {
; #pragma unroll
;                 for (int r = 0; r < 16; ++r) {
;                     const int key = kbase + 8 * (r >> 2) + (r & 3);
;                     if (key > t) s0[r] = -INFINITY;
;                     if (key + 32 > t) s1[r] = -INFINITY;
;                 }
;             }
.LBB0_178:
	v_add_u32_e32 v14, v134, v135
	v_add_u32_e32 v0, v136, v135
	v_add_u32_e32 v156, v138, v139
	ds_read_b128 v[170:173], v14 offset:0
	ds_read_b128 v[174:177], v0 offset:0
	ds_read_b128 v[178:181], v14 offset:32
	ds_read_b128 v[182:185], v0 offset:32
	ds_read_b128 v[186:189], v14 offset:64
	ds_read_b128 v[194:197], v0 offset:64
	ds_read_b128 v[198:201], v14 offset:96
	ds_read_b128 v[202:205], v0 offset:96
	ds_read_b128 v[144:147], v135 offset:43008
	ds_read_b128 v[148:151], v135 offset:43040
	ds_read_b128 v[152:155], v135 offset:43072
	ds_read_b128 v[12:15], v135 offset:43104
	s_or_b32 s1, s0, 63
	v_cmp_gt_i32_e32 vcc, s1, v125
	s_waitcnt lgkmcnt(11)
	v_mfma_f32_32x32x16_bf16 v[80:95], v[170:173], v[104:107], v[48:63]
	ds_read_b64_tr_b16 v[206:207], v156 offset:18432
	ds_read_b64_tr_b16 v[208:209], v156 offset:19968
	s_waitcnt lgkmcnt(12)
	v_mfma_f32_32x32x16_bf16 v[64:79], v[174:177], v[104:107], v[48:63]
	ds_read_b64_tr_b16 v[210:211], v156 offset:21504
	ds_read_b64_tr_b16 v[212:213], v156 offset:23040
	s_waitcnt lgkmcnt(13)
	v_mfma_f32_32x32x16_bf16 v[80:95], v[178:181], v[96:99], v[80:95]
	ds_read_b64_tr_b16 v[226:227], v156 offset:24576
	ds_read_b64_tr_b16 v[228:229], v156 offset:26112
	s_waitcnt lgkmcnt(14)
	v_mfma_f32_32x32x16_bf16 v[64:79], v[182:185], v[96:99], v[64:79]
	ds_read_b64_tr_b16 v[230:231], v156 offset:27648
	ds_read_b64_tr_b16 v[232:233], v156 offset:29184
	s_waitcnt lgkmcnt(15)
	v_mfma_f32_32x32x16_bf16 v[80:95], v[186:189], v[100:103], v[80:95]
	ds_read_b64_tr_b16 v[234:235], v156 offset:18496
	ds_read_b64_tr_b16 v[236:237], v156 offset:20032
	s_waitcnt lgkmcnt(15)
	v_mfma_f32_32x32x16_bf16 v[64:79], v[194:197], v[100:103], v[64:79]
	ds_read_b64_tr_b16 v[238:239], v156 offset:21568
	ds_read_b64_tr_b16 v[240:241], v156 offset:23104
	v_cndmask_b32_e64 v0, 0, 1, vcc
	s_nop 0
	v_readfirstlane_b32 s1, v0
	s_bitcmp0_b32 s1, 0
	s_waitcnt lgkmcnt(15)
	v_mfma_f32_32x32x16_bf16 v[80:95], v[198:201], v[108:111], v[80:95]
	ds_read_b64_tr_b16 v[242:243], v156 offset:24640
	ds_read_b64_tr_b16 v[244:245], v156 offset:26176
	s_waitcnt lgkmcnt(15)
	v_mfma_f32_32x32x16_bf16 v[64:79], v[202:205], v[108:111], v[64:79]
	ds_read_b64_tr_b16 v[246:247], v156 offset:27712
	ds_read_b64_tr_b16 v[248:249], v156 offset:29248
	s_waitcnt lgkmcnt(3)
	s_nop 5
	v_fma_f32 v82, v82, s54, v146
	v_fma_f32 v83, v83, s54, v147
	s_waitcnt lgkmcnt(2)
	v_fma_f32 v86, v86, s54, v150
	v_fma_f32 v87, v87, s54, v151
	s_waitcnt lgkmcnt(1)
	v_fma_f32 v88, v88, s54, v152
	v_fma_f32 v89, v89, s54, v153
	s_waitcnt lgkmcnt(0)
	v_fma_f32 v10, v94, s54, v14
	v_fma_f32 v11, v95, s54, v15
	v_fma_f32 v12, v92, s54, v12
	v_fma_f32 v13, v93, s54, v13
	v_fma_f32 v14, v90, s54, v154
	v_fma_f32 v15, v91, s54, v155
	v_fma_f32 v84, v84, s54, v148
	v_fma_f32 v85, v85, s54, v149
	v_fma_f32 v80, v80, s54, v144
	v_fma_f32 v81, v81, s54, v145
	ds_read_b128 v[90:93], v135 offset:43136
	ds_read_b128 v[144:147], v135 offset:43168
	ds_read_b128 v[148:151], v135 offset:43200
	ds_read_b128 v[152:155], v135 offset:43232
	s_waitcnt lgkmcnt(3)
	v_fma_f32 v66, v66, s54, v92
	v_fma_f32 v67, v67, s54, v93
	s_waitcnt lgkmcnt(2)
	v_fma_f32 v70, v70, s54, v146
	v_fma_f32 v71, v71, s54, v147
	s_waitcnt lgkmcnt(1)
	v_fma_f32 v74, v74, s54, v150
	v_fma_f32 v75, v75, s54, v151
	s_waitcnt lgkmcnt(0)
	v_fma_f32 v78, v78, s54, v154
	v_fma_f32 v79, v79, s54, v155
	v_fma_f32 v76, v76, s54, v152
	v_fma_f32 v77, v77, s54, v153
	v_fma_f32 v72, v72, s54, v148
	v_fma_f32 v73, v73, s54, v149
	v_fma_f32 v68, v68, s54, v144
	v_fma_f32 v69, v69, s54, v145
	v_fma_f32 v64, v64, s54, v90
	v_fma_f32 v65, v65, s54, v91
	s_cbranch_scc1 .LBB0_180
	v_or_b32_e32 v0, s0, v137
	v_or_b32_e32 v90, 32, v0
	v_cmp_le_i32_e32 vcc, v90, v126
	v_or_b32_e32 v90, 33, v0
	s_nop 0
	v_cndmask_b32_e32 v64, v220, v64, vcc
	v_cmp_lt_i32_e32 vcc, v0, v126
	s_nop 1
	v_cndmask_b32_e32 v81, v220, v81, vcc
	v_cmp_le_i32_e32 vcc, v0, v126
	s_nop 1
	v_cndmask_b32_e32 v80, v220, v80, vcc
	v_cmp_le_i32_e32 vcc, v90, v126
	v_or_b32_e32 v90, 2, v0
	s_nop 0
	v_cndmask_b32_e32 v65, v220, v65, vcc
	v_cmp_le_i32_e32 vcc, v90, v126
	v_or_b32_e32 v90, 34, v0
	s_nop 0
	v_cndmask_b32_e32 v82, v220, v82, vcc
	v_cmp_le_i32_e32 vcc, v90, v126
	v_or_b32_e32 v90, 3, v0
	s_nop 0
	v_cndmask_b32_e32 v66, v220, v66, vcc
	v_cmp_le_i32_e32 vcc, v90, v126
	v_or_b32_e32 v90, 35, v0
	s_nop 0
	v_cndmask_b32_e32 v83, v220, v83, vcc
	v_cmp_le_i32_e32 vcc, v90, v126
	v_or_b32_e32 v90, 8, v0
	s_nop 0
	v_cndmask_b32_e32 v67, v220, v67, vcc
	v_cmp_le_i32_e32 vcc, v90, v126
	v_or_b32_e32 v90, 40, v0
	s_nop 0
	v_cndmask_b32_e32 v84, v220, v84, vcc
	v_cmp_le_i32_e32 vcc, v90, v126
	v_or_b32_e32 v90, 9, v0
	s_nop 0
	v_cndmask_b32_e32 v68, v220, v68, vcc
	v_cmp_le_i32_e32 vcc, v90, v126
	v_or_b32_e32 v90, 41, v0
	s_nop 0
	v_cndmask_b32_e32 v85, v220, v85, vcc
	v_cmp_le_i32_e32 vcc, v90, v126
	v_or_b32_e32 v90, 10, v0
	s_nop 0
	v_cndmask_b32_e32 v69, v220, v69, vcc
	v_cmp_le_i32_e32 vcc, v90, v126
	v_or_b32_e32 v90, 42, v0
	s_nop 0
	v_cndmask_b32_e32 v86, v220, v86, vcc
	v_cmp_le_i32_e32 vcc, v90, v126
	v_or_b32_e32 v90, 11, v0
	s_nop 0
	v_cndmask_b32_e32 v70, v220, v70, vcc
	v_cmp_le_i32_e32 vcc, v90, v126
	v_or_b32_e32 v90, 43, v0
	s_nop 0
	v_cndmask_b32_e32 v87, v220, v87, vcc
	v_cmp_le_i32_e32 vcc, v90, v126
	v_or_b32_e32 v90, 16, v0
	s_nop 0
	v_cndmask_b32_e32 v71, v220, v71, vcc
	v_cmp_le_i32_e32 vcc, v90, v126
	v_or_b32_e32 v90, 48, v0
	s_nop 0
	v_cndmask_b32_e32 v88, v220, v88, vcc
	v_cmp_le_i32_e32 vcc, v90, v126
	v_or_b32_e32 v90, 17, v0
	s_nop 0
	v_cndmask_b32_e32 v72, v220, v72, vcc
	v_cmp_le_i32_e32 vcc, v90, v126
	v_or_b32_e32 v90, 49, v0
	s_nop 0
	v_cndmask_b32_e32 v89, v220, v89, vcc
	v_cmp_le_i32_e32 vcc, v90, v126
	v_or_b32_e32 v90, 18, v0
	s_nop 0
	v_cndmask_b32_e32 v73, v220, v73, vcc
	v_cmp_le_i32_e32 vcc, v90, v126
	v_or_b32_e32 v90, 50, v0
	s_nop 0
	v_cndmask_b32_e32 v14, v220, v14, vcc
	v_cmp_le_i32_e32 vcc, v90, v126
	v_or_b32_e32 v90, 19, v0
	s_nop 0
	v_cndmask_b32_e32 v74, v220, v74, vcc
	v_cmp_le_i32_e32 vcc, v90, v126
	v_or_b32_e32 v90, 51, v0
	s_nop 0
	v_cndmask_b32_e32 v15, v220, v15, vcc
	v_cmp_le_i32_e32 vcc, v90, v126
	v_or_b32_e32 v90, 24, v0
	s_nop 0
	v_cndmask_b32_e32 v75, v220, v75, vcc
	v_cmp_le_i32_e32 vcc, v90, v126
	v_or_b32_e32 v90, 56, v0
	s_nop 0
	v_cndmask_b32_e32 v12, v220, v12, vcc
	v_cmp_le_i32_e32 vcc, v90, v126
	v_or_b32_e32 v90, 25, v0
	s_nop 0
	v_cndmask_b32_e32 v76, v220, v76, vcc
	v_cmp_le_i32_e32 vcc, v90, v126
	v_or_b32_e32 v90, 57, v0
	s_nop 0
	v_cndmask_b32_e32 v13, v220, v13, vcc
	v_cmp_le_i32_e32 vcc, v90, v126
	v_or_b32_e32 v90, 26, v0
	s_nop 0
	v_cndmask_b32_e32 v77, v220, v77, vcc
	v_cmp_le_i32_e32 vcc, v90, v126
	v_or_b32_e32 v90, 58, v0
	s_nop 0
	v_cndmask_b32_e32 v10, v220, v10, vcc
	v_cmp_le_i32_e32 vcc, v90, v126
	v_or_b32_e32 v90, 27, v0
	v_or_b32_e32 v0, 59, v0
	v_cndmask_b32_e32 v78, v220, v78, vcc
	v_cmp_le_i32_e32 vcc, v90, v126
	s_nop 1
	v_cndmask_b32_e32 v11, v220, v11, vcc
	v_cmp_le_i32_e32 vcc, v0, v126
	s_nop 1
	v_cndmask_b32_e32 v79, v220, v79, vcc
; __device__ __forceinline__ float ex2(float x) { return __builtin_amdgcn_exp2f(x); }
; __device__ __forceinline__ float half_max(float x) { auto rr = __builtin_amdgcn_permlane32_swap(__float_as_uint(x), __float_as_uint(x), false, false); return fmaxf(__uint_as_float(rr[0]), __uint_as_float(rr[1])); }
; __device__ __forceinline__ float max3f(float a, float b, float c) { float r; asm("v_max3_f32 %0, %1, %2, %3" : "=v"(r) : "v"(a), "v"(b), "v"(c)); return r; }
; template <int MODE> ...
;     ...
;         if (MODE != MODE_CMP2) {
;             float mx = max3f(s0[0], s1[0], s0[1]);
; #pragma unroll
;             for (int r = 1; r < 15; r += 2) { mx = max3f(mx, s1[r], s0[r + 1]); mx = max3f(mx, s1[r + 1], (r + 2 < 16) ? s0[r + 2] : s1[r + 1]); }
;             mx = fmaxf(mx, s1[15]);
;             mx = half_max(mx);
;             const bool minf = (m == -INFINITY);
;             if (__any((mx > RESC_THR) || (minf && mx > -INFINITY))) {
;                 const float delta = minf ? ((mx == -INFINITY) ? 0.f : mx) : fmaxf(mx, 0.f);
;                 m = (minf && mx == -INFINITY) ? -INFINITY : mref + delta;
;                 { const float nm = (m == -INFINITY) ? 0.f : -m * (1.0f / SC2);
; #pragma unroll
;                   for (int r = 0; r < 16; ++r) negm[r] = nm; }
;                 const float alpha = minf ? 1.f : ex2(-delta);
;                 l *= alpha;
;                 if (MODE != MODE_CMP1) { o[0] = o[0] * alpha; o[1] = o[1] * alpha; }
; #pragma unroll
;                 for (int r = 0; r < 16; ++r) { s0[r] -= delta; s1[r] -= delta; }
;             }
.LBB0_180:
	v_max3_f32 v0, v80, v64, v81
	v_max_f32_e32 v90, v79, v79
	v_max3_f32 v0, v0, v65, v82
	v_cmp_eq_f32_e64 s[0:1], s16, v142
	v_max3_f32 v0, v0, v66, v83
	v_max3_f32 v0, v0, v67, v84
	v_max3_f32 v0, v0, v68, v85
	v_max3_f32 v0, v0, v69, v86
	v_max3_f32 v0, v0, v70, v87
	v_max3_f32 v0, v0, v71, v88
	v_max3_f32 v0, v0, v72, v89
	v_max3_f32 v0, v0, v73, v14
	v_max3_f32 v0, v0, v74, v15
	v_max3_f32 v0, v0, v75, v12
	v_max3_f32 v0, v0, v76, v13
	v_max3_f32 v0, v0, v77, v10
	v_max3_f32 v0, v0, v78, v11
	v_max_f32_e32 v0, v0, v0
	v_max_f32_e32 v0, v0, v90
	v_mov_b32_e32 v90, v0
	s_nop 1
	v_permlane32_swap_b32_e32 v0, v90
	v_max_f32_e32 v90, v90, v90
	v_max_f32_e32 v0, v0, v0
	v_max_f32_e32 v0, v0, v90
	v_cmp_lg_f32_e64 s[40:41], s16, v0
	v_cmp_lt_f32_e32 vcc, s17, v0
	s_and_b64 s[40:41], s[0:1], s[40:41]
	s_or_b64 vcc, vcc, s[40:41]
	s_cbranch_vccz .LBB0_182
	v_cmp_eq_f32_e32 vcc, s16, v0
	v_cndmask_b32_e64 v48, v142, 0, s[0:1]
	s_nop 0
	v_cndmask_b32_e64 v49, v0, 0, vcc
	v_max_f32_e32 v0, v0, v0
	v_max_f32_e32 v0, 0, v0
	v_cndmask_b32_e64 v0, v0, v49, s[0:1]
	v_exp_f32_e64 v90, -v0
	v_add_f32_e32 v48, v48, v0
	s_and_b64 vcc, s[0:1], vcc
	v_cndmask_b32_e32 v142, v48, v220, vcc
	v_mul_f32_e32 v48, 0xc0b17218, v142
	v_cmp_neq_f32_e32 vcc, s16, v142
	v_cndmask_b32_e64 v90, v90, 1.0, s[0:1]
	v_mul_f32_e32 v140, v140, v90
	v_cndmask_b32_e32 v48, 0, v48, vcc
	v_mov_b32_e32 v49, v48
	v_mov_b32_e32 v50, v48
	v_mov_b32_e32 v51, v48
	v_mov_b32_e32 v52, v48
	v_mov_b32_e32 v53, v48
	v_mov_b32_e32 v54, v48
	v_mov_b32_e32 v55, v48
	v_mov_b32_e32 v56, v48
	v_mov_b32_e32 v57, v48
	v_mov_b32_e32 v58, v48
	v_mov_b32_e32 v59, v48
	v_mov_b32_e32 v60, v48
	v_mov_b32_e32 v61, v48
	v_mov_b32_e32 v62, v48
	v_mov_b32_e32 v63, v48
	v_pk_mul_f32 v[46:47], v[46:47], v[90:91] op_sel_hi:[1,0]
	v_pk_mul_f32 v[44:45], v[44:45], v[90:91] op_sel_hi:[1,0]
	v_pk_mul_f32 v[42:43], v[42:43], v[90:91] op_sel_hi:[1,0]
	v_pk_mul_f32 v[40:41], v[40:41], v[90:91] op_sel_hi:[1,0]
	v_pk_mul_f32 v[38:39], v[38:39], v[90:91] op_sel_hi:[1,0]
	v_pk_mul_f32 v[36:37], v[36:37], v[90:91] op_sel_hi:[1,0]
	v_pk_mul_f32 v[34:35], v[34:35], v[90:91] op_sel_hi:[1,0]
	v_pk_mul_f32 v[32:33], v[32:33], v[90:91] op_sel_hi:[1,0]
	v_pk_mul_f32 v[30:31], v[30:31], v[90:91] op_sel_hi:[1,0]
	v_pk_mul_f32 v[28:29], v[28:29], v[90:91] op_sel_hi:[1,0]
	v_pk_mul_f32 v[26:27], v[26:27], v[90:91] op_sel_hi:[1,0]
	v_pk_mul_f32 v[24:25], v[24:25], v[90:91] op_sel_hi:[1,0]
	v_pk_mul_f32 v[22:23], v[22:23], v[90:91] op_sel_hi:[1,0]
	v_pk_mul_f32 v[20:21], v[20:21], v[90:91] op_sel_hi:[1,0]
	v_pk_mul_f32 v[18:19], v[18:19], v[90:91] op_sel_hi:[1,0]
	v_pk_mul_f32 v[16:17], v[16:17], v[90:91] op_sel_hi:[1,0]
	v_pk_add_f32 v[80:81], v[80:81], v[0:1] op_sel_hi:[1,0] neg_lo:[0,1] neg_hi:[0,1]
	v_pk_add_f32 v[64:65], v[64:65], v[0:1] op_sel_hi:[1,0] neg_lo:[0,1] neg_hi:[0,1]
	v_pk_add_f32 v[82:83], v[82:83], v[0:1] op_sel_hi:[1,0] neg_lo:[0,1] neg_hi:[0,1]
	v_pk_add_f32 v[66:67], v[66:67], v[0:1] op_sel_hi:[1,0] neg_lo:[0,1] neg_hi:[0,1]
	v_pk_add_f32 v[84:85], v[84:85], v[0:1] op_sel_hi:[1,0] neg_lo:[0,1] neg_hi:[0,1]
	v_pk_add_f32 v[68:69], v[68:69], v[0:1] op_sel_hi:[1,0] neg_lo:[0,1] neg_hi:[0,1]
	v_pk_add_f32 v[86:87], v[86:87], v[0:1] op_sel_hi:[1,0] neg_lo:[0,1] neg_hi:[0,1]
	v_pk_add_f32 v[70:71], v[70:71], v[0:1] op_sel_hi:[1,0] neg_lo:[0,1] neg_hi:[0,1]
	v_pk_add_f32 v[88:89], v[88:89], v[0:1] op_sel_hi:[1,0] neg_lo:[0,1] neg_hi:[0,1]
	v_pk_add_f32 v[72:73], v[72:73], v[0:1] op_sel_hi:[1,0] neg_lo:[0,1] neg_hi:[0,1]
	v_pk_add_f32 v[14:15], v[14:15], v[0:1] op_sel_hi:[1,0] neg_lo:[0,1] neg_hi:[0,1]
	v_pk_add_f32 v[74:75], v[74:75], v[0:1] op_sel_hi:[1,0] neg_lo:[0,1] neg_hi:[0,1]
	v_pk_add_f32 v[12:13], v[12:13], v[0:1] op_sel_hi:[1,0] neg_lo:[0,1] neg_hi:[0,1]
	v_pk_add_f32 v[76:77], v[76:77], v[0:1] op_sel_hi:[1,0] neg_lo:[0,1] neg_hi:[0,1]
	v_pk_add_f32 v[10:11], v[10:11], v[0:1] op_sel_hi:[1,0] neg_lo:[0,1] neg_hi:[0,1]
	v_pk_add_f32 v[78:79], v[78:79], v[0:1] op_sel_hi:[1,0] neg_lo:[0,1] neg_hi:[0,1]

; __device__ __forceinline__ f32x16 mfma32(bf16x8 a, bf16x8 b, f32x16 c) { return __builtin_amdgcn_mfma_f32_32x32x16_bf16(a, b, c, 0, 0, 0); }
; template <int MODE> ...
;     ...
;         const lptr Kt = L + A_KT + buf * 9216, Vt = L + A_VT + vcur * 12288;
;         f32x16 s0, s1;
; #pragma unroll
;         for (int s4 = 0; s4 < 4; ++s4) {
;             const bf16x8 a0 = lds_ld<bf16x8>(Kt + n * KP + s4 * 32 + hl * 16);
;             const bf16x8 a1 = lds_ld<bf16x8>(Kt + (32 + n) * KP + s4 * 32 + hl * 16);
;             if (s4 == 0) { s0 = mfma32(a0, qf[0], negm); s1 = mfma32(a1, qf[0], negm); }
;             else { s0 = mfma32(a0, qf[s4], s0); s1 = mfma32(a1, qf[s4], s1); }
;         }
;         const int kbase = 64 * kt + 4 * hl;
;         const bool far = (MODE == MODE_WIN || MODE == MODE_SEL) ? (wtmin - (64 * kt + 63) >= 128) : false;
;         const bool fmask = (MODE == MODE_FOX) ? (64 * kt + 63 > wtmin) : false;
;         const bool clean = (MODE == MODE_WIN) ? (far && (wtmax - 64 * kt < W)) : false;
;         const float mref = (MODE == MODE_CMP2) ? mfix : ((m == -INFINITY) ? 0.f : m);
;         if (MODE == MODE_FOX) {
; #pragma unroll
;             for (int kb = 0; kb < 2; ++kb)
; #pragma unroll
;                 for (int a = 0; a < 4; ++a) {
;                     const f32x4 c4 = lds_ld<f32x4>(L + A_CB + buf * 256 + (32 * kb + 8 * a + 4 * hl) * 4);
; #pragma unroll
;                     for (int e = 0; e < 4; ++e) { const int r = 4 * a + e; if (kb) s1[r] = s1[r] * SC2 + c4[e]; else s0[r] = s0[r] * SC2 + c4[e]; }
;                 }
;             if (__builtin_amdgcn_readfirstlane((int)fmask)) {
; #pragma unroll
;                 for (int r = 0; r < 16; ++r) {
;                     const int key = kbase + 8 * (r >> 2) + (r & 3);
;                     if (key > t) s0[r] = -INFINITY;
;                     if (key + 32 > t) s1[r] = -INFINITY;
;                 }
;             }
.LBB0_194:
	v_add_u32_e32 v14, v134, v135
	v_add_u32_e32 v0, v136, v135
	v_add_u32_e32 v156, v138, v139
	ds_read_b128 v[170:173], v14 offset:9216
	ds_read_b128 v[174:177], v0 offset:9216
	ds_read_b128 v[178:181], v14 offset:9248
	ds_read_b128 v[182:185], v0 offset:9248
	ds_read_b128 v[186:189], v14 offset:9280
	ds_read_b128 v[194:197], v0 offset:9280
	ds_read_b128 v[198:201], v14 offset:9312
	ds_read_b128 v[202:205], v0 offset:9312
	ds_read_b128 v[144:147], v135 offset:43264
	ds_read_b128 v[148:151], v135 offset:43296
	ds_read_b128 v[152:155], v135 offset:43328
	ds_read_b128 v[12:15], v135 offset:43360
	s_or_b32 s1, s0, 63
	v_cmp_gt_i32_e32 vcc, s1, v125
	s_waitcnt lgkmcnt(11)
	v_mfma_f32_32x32x16_bf16 v[80:95], v[170:173], v[104:107], v[48:63]
	ds_read_b64_tr_b16 v[206:207], v156 offset:30720
	ds_read_b64_tr_b16 v[208:209], v156 offset:32256
	s_waitcnt lgkmcnt(12)
	v_mfma_f32_32x32x16_bf16 v[64:79], v[174:177], v[104:107], v[48:63]
	ds_read_b64_tr_b16 v[210:211], v156 offset:33792
	ds_read_b64_tr_b16 v[212:213], v156 offset:35328
	s_waitcnt lgkmcnt(13)
	v_mfma_f32_32x32x16_bf16 v[80:95], v[178:181], v[96:99], v[80:95]
	ds_read_b64_tr_b16 v[226:227], v156 offset:36864
	ds_read_b64_tr_b16 v[228:229], v156 offset:38400
	s_waitcnt lgkmcnt(14)
	v_mfma_f32_32x32x16_bf16 v[64:79], v[182:185], v[96:99], v[64:79]
	ds_read_b64_tr_b16 v[230:231], v156 offset:39936
	ds_read_b64_tr_b16 v[232:233], v156 offset:41472
	s_waitcnt lgkmcnt(15)
	v_mfma_f32_32x32x16_bf16 v[80:95], v[186:189], v[100:103], v[80:95]
	ds_read_b64_tr_b16 v[234:235], v156 offset:30784
	ds_read_b64_tr_b16 v[236:237], v156 offset:32320
	s_waitcnt lgkmcnt(15)
	v_mfma_f32_32x32x16_bf16 v[64:79], v[194:197], v[100:103], v[64:79]
	ds_read_b64_tr_b16 v[238:239], v156 offset:33856
	ds_read_b64_tr_b16 v[240:241], v156 offset:35392
	v_cndmask_b32_e64 v0, 0, 1, vcc
	s_nop 0
	v_readfirstlane_b32 s1, v0
	s_bitcmp0_b32 s1, 0
	s_waitcnt lgkmcnt(15)
	v_mfma_f32_32x32x16_bf16 v[80:95], v[198:201], v[108:111], v[80:95]
	ds_read_b64_tr_b16 v[242:243], v156 offset:36928
	ds_read_b64_tr_b16 v[244:245], v156 offset:38464
	s_waitcnt lgkmcnt(15)
	v_mfma_f32_32x32x16_bf16 v[64:79], v[202:205], v[108:111], v[64:79]
	ds_read_b64_tr_b16 v[246:247], v156 offset:40000
	ds_read_b64_tr_b16 v[248:249], v156 offset:41536
	s_waitcnt lgkmcnt(3)
	s_nop 5
	v_fma_f32 v82, v82, s54, v146
	v_fma_f32 v83, v83, s54, v147
	s_waitcnt lgkmcnt(2)
	v_fma_f32 v86, v86, s54, v150
	v_fma_f32 v87, v87, s54, v151
	s_waitcnt lgkmcnt(1)
	v_fma_f32 v88, v88, s54, v152
	v_fma_f32 v89, v89, s54, v153
	s_waitcnt lgkmcnt(0)
	v_fma_f32 v10, v94, s54, v14
	v_fma_f32 v11, v95, s54, v15
	v_fma_f32 v12, v92, s54, v12
	v_fma_f32 v13, v93, s54, v13
	v_fma_f32 v14, v90, s54, v154
	v_fma_f32 v15, v91, s54, v155
	v_fma_f32 v84, v84, s54, v148
	v_fma_f32 v85, v85, s54, v149
	v_fma_f32 v80, v80, s54, v144
	v_fma_f32 v81, v81, s54, v145
	ds_read_b128 v[90:93], v135 offset:43392
	ds_read_b128 v[144:147], v135 offset:43424
	ds_read_b128 v[148:151], v135 offset:43456
	ds_read_b128 v[152:155], v135 offset:43488
	s_waitcnt lgkmcnt(3)
	v_fma_f32 v66, v66, s54, v92
	v_fma_f32 v67, v67, s54, v93
	s_waitcnt lgkmcnt(2)
	v_fma_f32 v70, v70, s54, v146
	v_fma_f32 v71, v71, s54, v147
	s_waitcnt lgkmcnt(1)
	v_fma_f32 v74, v74, s54, v150
	v_fma_f32 v75, v75, s54, v151
	s_waitcnt lgkmcnt(0)
	v_fma_f32 v78, v78, s54, v154
	v_fma_f32 v79, v79, s54, v155
	v_fma_f32 v76, v76, s54, v152
	v_fma_f32 v77, v77, s54, v153
	v_fma_f32 v72, v72, s54, v148
	v_fma_f32 v73, v73, s54, v149
	v_fma_f32 v68, v68, s54, v144
	v_fma_f32 v69, v69, s54, v145
	v_fma_f32 v64, v64, s54, v90
	v_fma_f32 v65, v65, s54, v91
	s_cbranch_scc1 .LBB0_196
	v_or_b32_e32 v0, s0, v137
	v_or_b32_e32 v90, 32, v0
	v_cmp_le_i32_e32 vcc, v90, v126
	v_or_b32_e32 v90, 33, v0
	s_nop 0
	v_cndmask_b32_e32 v64, v220, v64, vcc
	v_cmp_lt_i32_e32 vcc, v0, v126
	s_nop 1
	v_cndmask_b32_e32 v81, v220, v81, vcc
	v_cmp_le_i32_e32 vcc, v0, v126
	s_nop 1
	v_cndmask_b32_e32 v80, v220, v80, vcc
	v_cmp_le_i32_e32 vcc, v90, v126
	v_or_b32_e32 v90, 2, v0
	s_nop 0
	v_cndmask_b32_e32 v65, v220, v65, vcc
	v_cmp_le_i32_e32 vcc, v90, v126
	v_or_b32_e32 v90, 34, v0
	s_nop 0
	v_cndmask_b32_e32 v82, v220, v82, vcc
	v_cmp_le_i32_e32 vcc, v90, v126
	v_or_b32_e32 v90, 3, v0
	s_nop 0
	v_cndmask_b32_e32 v66, v220, v66, vcc
	v_cmp_le_i32_e32 vcc, v90, v126
	v_or_b32_e32 v90, 35, v0
	s_nop 0
	v_cndmask_b32_e32 v83, v220, v83, vcc
	v_cmp_le_i32_e32 vcc, v90, v126
	v_or_b32_e32 v90, 8, v0
	s_nop 0
	v_cndmask_b32_e32 v67, v220, v67, vcc
	v_cmp_le_i32_e32 vcc, v90, v126
	v_or_b32_e32 v90, 40, v0
	s_nop 0
	v_cndmask_b32_e32 v84, v220, v84, vcc
	v_cmp_le_i32_e32 vcc, v90, v126
	v_or_b32_e32 v90, 9, v0
	s_nop 0
	v_cndmask_b32_e32 v68, v220, v68, vcc
	v_cmp_le_i32_e32 vcc, v90, v126
	v_or_b32_e32 v90, 41, v0
	s_nop 0
	v_cndmask_b32_e32 v85, v220, v85, vcc
	v_cmp_le_i32_e32 vcc, v90, v126
	v_or_b32_e32 v90, 10, v0
	s_nop 0
	v_cndmask_b32_e32 v69, v220, v69, vcc
	v_cmp_le_i32_e32 vcc, v90, v126
	v_or_b32_e32 v90, 42, v0
	s_nop 0
	v_cndmask_b32_e32 v86, v220, v86, vcc
	v_cmp_le_i32_e32 vcc, v90, v126
	v_or_b32_e32 v90, 11, v0
	s_nop 0
	v_cndmask_b32_e32 v70, v220, v70, vcc
	v_cmp_le_i32_e32 vcc, v90, v126
	v_or_b32_e32 v90, 43, v0
	s_nop 0
	v_cndmask_b32_e32 v87, v220, v87, vcc
	v_cmp_le_i32_e32 vcc, v90, v126
	v_or_b32_e32 v90, 16, v0
	s_nop 0
	v_cndmask_b32_e32 v71, v220, v71, vcc
	v_cmp_le_i32_e32 vcc, v90, v126
	v_or_b32_e32 v90, 48, v0
	s_nop 0
	v_cndmask_b32_e32 v88, v220, v88, vcc
	v_cmp_le_i32_e32 vcc, v90, v126
	v_or_b32_e32 v90, 17, v0
	s_nop 0
	v_cndmask_b32_e32 v72, v220, v72, vcc
	v_cmp_le_i32_e32 vcc, v90, v126
	v_or_b32_e32 v90, 49, v0
	s_nop 0
	v_cndmask_b32_e32 v89, v220, v89, vcc
	v_cmp_le_i32_e32 vcc, v90, v126
	v_or_b32_e32 v90, 18, v0
	s_nop 0
	v_cndmask_b32_e32 v73, v220, v73, vcc
	v_cmp_le_i32_e32 vcc, v90, v126
	v_or_b32_e32 v90, 50, v0
	s_nop 0
	v_cndmask_b32_e32 v14, v220, v14, vcc
	v_cmp_le_i32_e32 vcc, v90, v126
	v_or_b32_e32 v90, 19, v0
	s_nop 0
	v_cndmask_b32_e32 v74, v220, v74, vcc
	v_cmp_le_i32_e32 vcc, v90, v126
	v_or_b32_e32 v90, 51, v0
	s_nop 0
	v_cndmask_b32_e32 v15, v220, v15, vcc
	v_cmp_le_i32_e32 vcc, v90, v126
	v_or_b32_e32 v90, 24, v0
	s_nop 0
	v_cndmask_b32_e32 v75, v220, v75, vcc
	v_cmp_le_i32_e32 vcc, v90, v126
	v_or_b32_e32 v90, 56, v0
	s_nop 0
	v_cndmask_b32_e32 v12, v220, v12, vcc
	v_cmp_le_i32_e32 vcc, v90, v126
	v_or_b32_e32 v90, 25, v0
	s_nop 0
	v_cndmask_b32_e32 v76, v220, v76, vcc
	v_cmp_le_i32_e32 vcc, v90, v126
	v_or_b32_e32 v90, 57, v0
	s_nop 0
	v_cndmask_b32_e32 v13, v220, v13, vcc
	v_cmp_le_i32_e32 vcc, v90, v126
	v_or_b32_e32 v90, 26, v0
	s_nop 0
	v_cndmask_b32_e32 v77, v220, v77, vcc
	v_cmp_le_i32_e32 vcc, v90, v126
	v_or_b32_e32 v90, 58, v0
	s_nop 0
	v_cndmask_b32_e32 v10, v220, v10, vcc
	v_cmp_le_i32_e32 vcc, v90, v126
	v_or_b32_e32 v90, 27, v0
	v_or_b32_e32 v0, 59, v0
	v_cndmask_b32_e32 v78, v220, v78, vcc
	v_cmp_le_i32_e32 vcc, v90, v126
	s_nop 1
	v_cndmask_b32_e32 v11, v220, v11, vcc
	v_cmp_le_i32_e32 vcc, v0, v126
	s_nop 1
	v_cndmask_b32_e32 v79, v220, v79, vcc
